# final phase: out2 loads without nt hint (on top of P4 plain loads)
# speedup vs baseline: 1.0139x; 1.0010x over previous
; DI float bflo(unsigned w) { return __uint_as_float(w << 16); }
; DI float bfhi(unsigned w) { return __uint_as_float(w & 0xffff0000u); }
; DI void phase_final(const Params& p) {
;     ...
;     for (int row = (blockIdx.x * 8 + wid) * 2; row < S; row += gridDim.x * 16) {
;         f32x4 xv[2][8]; u32x2 yv[2][8]; float sq[2];
; #pragma unroll
;         for (int r = 0; r < 2; ++r) {
;             sq[r] = lane < 32 ? ssq[(size_t)(row + r) * 32 + lane] : 0.f;
; #pragma unroll
;             for (int i = 0; i < 8; ++i) { const size_t off = (size_t)(row + r) * DM + i * 256 + lane * 4; xv[r][i] = __builtin_nontemporal_load((const f32x4*)(x + off)); yv[r][i] = __builtin_nontemporal_load((const u32x2*)(o2 + off)); }
;         }
; #pragma unroll
;         for (int r = 0; r < 2; ++r) {
;             const float rs = rsqrtf(wave_sum(sq[r]) * (1.f / DM) + EPS);
; #pragma unroll
;             for (int i = 0; i < 8; ++i) { const size_t off = (size_t)(row + r) * DM + i * 256 + lane * 4;
;                 const f32x4 ov = {xv[r][i][0] + bflo(yv[r][i][0]) * rs * w[i][0], xv[r][i][1] + bfhi(yv[r][i][0]) * rs * w[i][1],
;                                   xv[r][i][2] + bflo(yv[r][i][1]) * rs * w[i][2], xv[r][i][3] + bfhi(yv[r][i][1]) * rs * w[i][3]};
;                 __builtin_nontemporal_store(ov, (f32x4*)(p.out + off)); }
;         }
;     }
.LBB0_598:
	s_or_b64 exec, exec, s[0:1]
	v_lshlrev_b64 v[108:109], 11, v[118:119]
	v_or_b32_e32 v108, v108, v100
	v_lshlrev_b64 v[34:35], 1, v[108:109]
	v_lshl_add_u64 v[32:33], v[108:109], 2, s[2:3]
	v_lshl_add_u64 v[36:37], s[4:5], 0, v[34:35]
	v_or_b32_e32 v38, 0x200, v34
	v_mov_b32_e32 v39, v35
	v_or_b32_e32 v40, 0x400, v34
	v_mov_b32_e32 v41, v35
	v_or_b32_e32 v34, 0x600, v34
	global_load_dwordx4 v[68:71], v[32:33], off nt
	global_load_dwordx4 v[56:59], v[32:33], off offset:1024 nt
	v_lshl_add_u64 v[38:39], s[4:5], 0, v[38:39]
	v_lshl_add_u64 v[40:41], s[4:5], 0, v[40:41]
	global_load_dwordx4 v[52:55], v[32:33], off offset:2048 nt
	global_load_dwordx4 v[48:51], v[32:33], off offset:3072 nt
	v_lshl_add_u64 v[32:33], s[4:5], 0, v[34:35]
	global_load_dwordx2 v[124:125], v[36:37], off
	global_load_dwordx2 v[122:123], v[38:39], off
	global_load_dwordx2 v[120:121], v[40:41], off
	global_load_dwordx2 v[116:117], v[32:33], off
	s_waitcnt vmcnt(0)
	ds_bpermute_b32 v149, v101, v127
	ds_bpermute_b32 v148, v101, v126
	v_or_b32_e32 v32, 0x400, v108
	v_mov_b32_e32 v33, v109
	v_lshl_add_u64 v[34:35], v[32:33], 2, s[2:3]
	v_lshl_add_u64 v[32:33], v[32:33], 1, s[4:5]
	s_waitcnt lgkmcnt(0)
	v_pk_add_f32 v[126:127], v[126:127], v[148:149]
	ds_bpermute_b32 v149, v107, v127
	ds_bpermute_b32 v148, v107, v126
	global_load_dwordx2 v[114:115], v[32:33], off
	global_load_dwordx4 v[44:47], v[34:35], off nt
	v_or_b32_e32 v32, 0x500, v108
	v_mov_b32_e32 v33, v109
	s_waitcnt lgkmcnt(0)
	v_pk_add_f32 v[126:127], v[126:127], v[148:149]
	ds_bpermute_b32 v149, v144, v127
	ds_bpermute_b32 v148, v144, v126
	v_lshl_add_u64 v[34:35], v[32:33], 2, s[2:3]
	v_lshl_add_u64 v[32:33], v[32:33], 1, s[4:5]
	global_load_dwordx2 v[112:113], v[32:33], off
	global_load_dwordx4 v[40:43], v[34:35], off nt
	v_or_b32_e32 v32, 0x600, v108
	v_mov_b32_e32 v33, v109
	s_waitcnt lgkmcnt(0)
	v_pk_add_f32 v[126:127], v[126:127], v[148:149]
	v_lshl_add_u64 v[34:35], v[32:33], 2, s[2:3]
	v_lshl_add_u64 v[32:33], v[32:33], 1, s[4:5]
	ds_bpermute_b32 v149, v145, v127
	ds_bpermute_b32 v148, v145, v126
	global_load_dwordx2 v[110:111], v[32:33], off
	global_load_dwordx4 v[36:39], v[34:35], off nt
	v_or_b32_e32 v108, 0x700, v108
	v_lshl_add_u64 v[32:33], v[108:109], 2, s[2:3]
	v_lshl_add_u64 v[108:109], v[108:109], 1, s[4:5]
	s_waitcnt lgkmcnt(0)
	v_pk_add_f32 v[126:127], v[126:127], v[148:149]
	global_load_dwordx2 v[108:109], v[108:109], off
	ds_bpermute_b32 v149, v146, v127
	ds_bpermute_b32 v148, v146, v126
	global_load_dwordx4 v[32:35], v[32:33], off nt
	v_lshlrev_b64 v[150:151], 13, v[96:97]
	v_lshlrev_b32_e32 v152, 16, v142
	v_and_b32_e32 v153, 0xffff0000, v142
	s_waitcnt lgkmcnt(0)
	v_pk_add_f32 v[126:127], v[126:127], v[148:149]
	ds_bpermute_b32 v149, v147, v127
	ds_bpermute_b32 v148, v147, v126
	v_lshlrev_b32_e32 v142, 16, v143
	v_and_b32_e32 v143, 0xffff0000, v143
	v_lshl_add_u64 v[154:155], v[104:105], 0, v[150:151]
	v_lshlrev_b32_e32 v156, 16, v140
	s_waitcnt lgkmcnt(0)
	v_pk_add_f32 v[126:127], v[126:127], v[148:149]
	v_and_b32_e32 v157, 0xffff0000, v140
	v_pk_fma_f32 v[126:127], v[126:127], s[10:11], v[106:107] op_sel_hi:[1,0,0]
	v_lshlrev_b32_e32 v140, 16, v141
	v_mul_f32_e32 v97, 0x4b800000, v127
	v_cmp_gt_f32_e64 s[0:1], s13, v127
	v_and_b32_e32 v141, 0xffff0000, v141
	v_lshl_add_u64 v[150:151], s[6:7], 0, v[150:151]
	v_cndmask_b32_e64 v97, v127, v97, s[0:1]
	v_rsq_f32_e32 v97, v97
	v_lshlrev_b32_e32 v98, 2, v100
	v_lshl_add_u64 v[150:151], v[150:151], 0, v[98:99]
	v_lshlrev_b32_e32 v158, 16, v138
	v_mul_f32_e32 v127, 0x45800000, v97
	v_cndmask_b32_e64 v148, v97, v127, s[0:1]
	v_pk_mul_f32 v[152:153], v[148:149], v[152:153] op_sel_hi:[0,1]
	v_pk_mul_f32 v[142:143], v[148:149], v[142:143] op_sel_hi:[0,1]
	v_pk_fma_f32 v[92:93], v[28:29], v[152:153], v[92:93]
	v_pk_fma_f32 v[94:95], v[30:31], v[142:143], v[94:95]
	global_store_dwordx4 v[154:155], v[92:95], off nt
	v_and_b32_e32 v159, 0xffff0000, v138
	v_lshlrev_b32_e32 v138, 16, v139
	v_pk_mul_f32 v[92:93], v[148:149], v[156:157] op_sel_hi:[0,1]
	v_pk_fma_f32 v[80:81], v[24:25], v[92:93], v[80:81]
	v_pk_mul_f32 v[92:93], v[148:149], v[140:141] op_sel_hi:[0,1]
	v_and_b32_e32 v139, 0xffff0000, v139
	v_pk_fma_f32 v[82:83], v[26:27], v[92:93], v[82:83]
	global_store_dwordx4 v[150:151], v[80:83], off offset:1024 nt
	v_lshlrev_b32_e32 v160, 16, v132
	v_and_b32_e32 v161, 0xffff0000, v132
	v_pk_mul_f32 v[80:81], v[148:149], v[158:159] op_sel_hi:[0,1]
	v_pk_mul_f32 v[82:83], v[148:149], v[138:139] op_sel_hi:[0,1]
	v_pk_fma_f32 v[80:81], v[20:21], v[80:81], v[84:85]
	v_pk_fma_f32 v[82:83], v[22:23], v[82:83], v[86:87]
	v_lshlrev_b32_e32 v132, 16, v133
	v_and_b32_e32 v133, 0xffff0000, v133
	global_store_dwordx4 v[150:151], v[80:83], off offset:2048 nt
	v_lshlrev_b32_e32 v162, 16, v136
	v_and_b32_e32 v163, 0xffff0000, v136
	v_pk_mul_f32 v[80:81], v[148:149], v[160:161] op_sel_hi:[0,1]
	v_pk_fma_f32 v[64:65], v[16:17], v[80:81], v[64:65]
	v_pk_mul_f32 v[80:81], v[148:149], v[132:133] op_sel_hi:[0,1]
	v_lshlrev_b32_e32 v136, 16, v137
	v_and_b32_e32 v137, 0xffff0000, v137
	v_pk_fma_f32 v[66:67], v[18:19], v[80:81], v[66:67]
	global_store_dwordx4 v[150:151], v[64:67], off offset:3072 nt
	v_add_co_u32_e64 v80, s[0:1], s11, v150
	s_nop 0
	v_pk_mul_f32 v[64:65], v[148:149], v[162:163] op_sel_hi:[0,1]
	v_pk_mul_f32 v[66:67], v[148:149], v[136:137] op_sel_hi:[0,1]
	v_lshlrev_b32_e32 v164, 16, v134
	v_and_b32_e32 v165, 0xffff0000, v134
	v_lshlrev_b32_e32 v134, 16, v135
	v_and_b32_e32 v135, 0xffff0000, v135
	v_pk_fma_f32 v[64:65], v[12:13], v[64:65], v[88:89]
; DI float bflo(unsigned w) { return __uint_as_float(w << 16); }
; DI float bfhi(unsigned w) { return __uint_as_float(w & 0xffff0000u); }
; DI void phase_final(const Params& p) {
;     ...
; #pragma unroll
;         for (int r = 0; r < 2; ++r) {
;             const float rs = rsqrtf(wave_sum(sq[r]) * (1.f / DM) + EPS);
; #pragma unroll
;             for (int i = 0; i < 8; ++i) { const size_t off = (size_t)(row + r) * DM + i * 256 + lane * 4;
;                 const f32x4 ov = {xv[r][i][0] + bflo(yv[r][i][0]) * rs * w[i][0], xv[r][i][1] + bfhi(yv[r][i][0]) * rs * w[i][1],
;                                   xv[r][i][2] + bflo(yv[r][i][1]) * rs * w[i][2], xv[r][i][3] + bfhi(yv[r][i][1]) * rs * w[i][3]};
;                 __builtin_nontemporal_store(ov, (f32x4*)(p.out + off)); }
;         }
	v_pk_fma_f32 v[66:67], v[14:15], v[66:67], v[90:91]
	v_addc_co_u32_e64 v81, s[0:1], 0, v151, s[0:1]
	global_store_dwordx4 v[80:81], v[64:67], off nt
	v_lshlrev_b32_e32 v166, 16, v130
	v_and_b32_e32 v167, 0xffff0000, v130
	v_pk_mul_f32 v[64:65], v[148:149], v[164:165] op_sel_hi:[0,1]
	v_pk_mul_f32 v[66:67], v[148:149], v[134:135] op_sel_hi:[0,1]
	v_lshlrev_b32_e32 v130, 16, v131
	v_and_b32_e32 v131, 0xffff0000, v131
	v_pk_fma_f32 v[64:65], v[8:9], v[64:65], v[76:77]
	v_pk_fma_f32 v[66:67], v[10:11], v[66:67], v[78:79]
	global_store_dwordx4 v[80:81], v[64:67], off offset:1024 nt
	v_lshlrev_b32_e32 v168, 16, v128
	v_and_b32_e32 v169, 0xffff0000, v128
	v_pk_mul_f32 v[64:65], v[148:149], v[166:167] op_sel_hi:[0,1]
	v_pk_mul_f32 v[66:67], v[148:149], v[130:131] op_sel_hi:[0,1]
	v_pk_fma_f32 v[64:65], v[4:5], v[64:65], v[72:73]
	v_pk_fma_f32 v[66:67], v[6:7], v[66:67], v[74:75]
	global_store_dwordx4 v[80:81], v[64:67], off offset:2048 nt
	v_cmp_gt_f32_e64 s[0:1], s13, v126
	v_lshlrev_b32_e32 v128, 16, v129
	v_pk_mul_f32 v[64:65], v[148:149], v[168:169] op_sel_hi:[0,1]
	v_pk_fma_f32 v[60:61], v[0:1], v[64:65], v[60:61]
	v_mul_f32_e32 v64, 0x4b800000, v126
	v_cndmask_b32_e64 v64, v126, v64, s[0:1]
	v_rsq_f32_e32 v66, v64
	v_and_b32_e32 v129, 0xffff0000, v129
	v_pk_mul_f32 v[64:65], v[148:149], v[128:129] op_sel_hi:[0,1]
	v_pk_fma_f32 v[62:63], v[2:3], v[64:65], v[62:63]
	global_store_dwordx4 v[80:81], v[60:63], off offset:3072 nt
	v_add_u32_e32 v96, s12, v96
	s_nop 0
	v_mul_f32_e32 v60, 0x45800000, v66
	v_cndmask_b32_e64 v64, v66, v60, s[0:1]
	v_lshlrev_b32_e32 v60, 16, v124
	v_and_b32_e32 v61, 0xffff0000, v124
	v_lshlrev_b32_e32 v62, 16, v125
	v_and_b32_e32 v63, 0xffff0000, v125
	v_lshlrev_b64 v[66:67], 13, v[118:119]
	v_pk_mul_f32 v[60:61], v[64:65], v[60:61] op_sel_hi:[0,1]
	v_pk_mul_f32 v[62:63], v[64:65], v[62:63] op_sel_hi:[0,1]
	v_pk_fma_f32 v[60:61], v[28:29], v[60:61], v[68:69]
	v_pk_fma_f32 v[62:63], v[30:31], v[62:63], v[70:71]
	v_lshl_add_u64 v[68:69], v[104:105], 0, v[66:67]
	global_store_dwordx4 v[68:69], v[60:63], off nt
	s_nop 1
	v_lshlrev_b32_e32 v60, 16, v122
	v_and_b32_e32 v61, 0xffff0000, v122
	v_pk_mul_f32 v[60:61], v[64:65], v[60:61] op_sel_hi:[0,1]
	v_pk_fma_f32 v[56:57], v[24:25], v[60:61], v[56:57]
	v_lshlrev_b32_e32 v60, 16, v123
	v_and_b32_e32 v61, 0xffff0000, v123
	v_pk_mul_f32 v[60:61], v[64:65], v[60:61] op_sel_hi:[0,1]
	v_pk_fma_f32 v[58:59], v[26:27], v[60:61], v[58:59]
	v_lshl_add_u64 v[60:61], s[6:7], 0, v[66:67]
	v_lshl_add_u64 v[60:61], v[60:61], 0, v[98:99]
	global_store_dwordx4 v[60:61], v[56:59], off offset:1024 nt
	s_nop 1
	v_lshlrev_b32_e32 v56, 16, v120
	v_and_b32_e32 v57, 0xffff0000, v120
	v_pk_mul_f32 v[56:57], v[64:65], v[56:57] op_sel_hi:[0,1]
	v_pk_fma_f32 v[52:53], v[20:21], v[56:57], v[52:53]
	v_lshlrev_b32_e32 v56, 16, v121
	v_and_b32_e32 v57, 0xffff0000, v121
	v_pk_mul_f32 v[56:57], v[64:65], v[56:57] op_sel_hi:[0,1]
	v_pk_fma_f32 v[54:55], v[22:23], v[56:57], v[54:55]
	global_store_dwordx4 v[60:61], v[52:55], off offset:2048 nt
	s_nop 1
	v_lshlrev_b32_e32 v52, 16, v116
	v_and_b32_e32 v53, 0xffff0000, v116
	v_pk_mul_f32 v[52:53], v[64:65], v[52:53] op_sel_hi:[0,1]
	v_pk_fma_f32 v[48:49], v[16:17], v[52:53], v[48:49]
	v_lshlrev_b32_e32 v52, 16, v117
	v_and_b32_e32 v53, 0xffff0000, v117
	v_pk_mul_f32 v[52:53], v[64:65], v[52:53] op_sel_hi:[0,1]
	v_pk_fma_f32 v[50:51], v[18:19], v[52:53], v[50:51]
	global_store_dwordx4 v[60:61], v[48:51], off offset:3072 nt
	s_waitcnt vmcnt(19)
	s_nop 0
	v_lshlrev_b32_e32 v48, 16, v114
	v_and_b32_e32 v49, 0xffff0000, v114
	v_pk_mul_f32 v[48:49], v[64:65], v[48:49] op_sel_hi:[0,1]
	s_waitcnt vmcnt(18)
	v_pk_fma_f32 v[44:45], v[12:13], v[48:49], v[44:45]
	v_lshlrev_b32_e32 v48, 16, v115
	v_and_b32_e32 v49, 0xffff0000, v115
	v_pk_mul_f32 v[48:49], v[64:65], v[48:49] op_sel_hi:[0,1]
	v_pk_fma_f32 v[46:47], v[14:15], v[48:49], v[46:47]
	v_add_co_u32_e64 v48, s[0:1], s11, v60
	s_nop 1
	v_addc_co_u32_e64 v49, s[0:1], 0, v61, s[0:1]
	global_store_dwordx4 v[48:49], v[44:47], off nt
	v_cmp_lt_i32_e64 s[0:1], s14, v96
	s_or_b64 s[8:9], s[0:1], s[8:9]
	s_waitcnt vmcnt(18)
	v_lshlrev_b32_e32 v44, 16, v112
	v_and_b32_e32 v45, 0xffff0000, v112
	v_pk_mul_f32 v[44:45], v[64:65], v[44:45] op_sel_hi:[0,1]
	s_waitcnt vmcnt(17)
	v_pk_fma_f32 v[40:41], v[8:9], v[44:45], v[40:41]
	v_lshlrev_b32_e32 v44, 16, v113
	v_and_b32_e32 v45, 0xffff0000, v113
	v_pk_mul_f32 v[44:45], v[64:65], v[44:45] op_sel_hi:[0,1]
	v_pk_fma_f32 v[42:43], v[10:11], v[44:45], v[42:43]
	global_store_dwordx4 v[48:49], v[40:43], off offset:1024 nt
	s_waitcnt vmcnt(17)
	s_nop 0
	v_lshlrev_b32_e32 v40, 16, v110
	v_and_b32_e32 v41, 0xffff0000, v110
	v_pk_mul_f32 v[40:41], v[64:65], v[40:41] op_sel_hi:[0,1]
	s_waitcnt vmcnt(16)
	v_pk_fma_f32 v[36:37], v[4:5], v[40:41], v[36:37]
	v_lshlrev_b32_e32 v40, 16, v111
	v_and_b32_e32 v41, 0xffff0000, v111
	v_pk_mul_f32 v[40:41], v[64:65], v[40:41] op_sel_hi:[0,1]
	v_pk_fma_f32 v[38:39], v[6:7], v[40:41], v[38:39]
	global_store_dwordx4 v[48:49], v[36:39], off offset:2048 nt
	s_waitcnt vmcnt(16)
	s_nop 0
	v_lshlrev_b32_e32 v36, 16, v108
	v_and_b32_e32 v37, 0xffff0000, v108
	v_pk_mul_f32 v[36:37], v[64:65], v[36:37] op_sel_hi:[0,1]
	s_waitcnt vmcnt(15)
	v_pk_fma_f32 v[32:33], v[0:1], v[36:37], v[32:33]
	v_lshlrev_b32_e32 v36, 16, v109
	v_and_b32_e32 v37, 0xffff0000, v109
	v_pk_mul_f32 v[36:37], v[64:65], v[36:37] op_sel_hi:[0,1]
	v_pk_fma_f32 v[34:35], v[2:3], v[36:37], v[34:35]
	global_store_dwordx4 v[48:49], v[32:35], off offset:3072 nt
	s_andn2_b64 exec, exec, s[8:9]
	s_cbranch_execz .LBB0_603

; DI void phase_final(const Params& p) {
;     ...
;         f32x4 xv[2][8]; u32x2 yv[2][8]; float sq[2];
; #pragma unroll
;         for (int r = 0; r < 2; ++r) {
;             sq[r] = lane < 32 ? ssq[(size_t)(row + r) * 32 + lane] : 0.f;
; #pragma unroll
;             for (int i = 0; i < 8; ++i) { const size_t off = (size_t)(row + r) * DM + i * 256 + lane * 4; xv[r][i] = __builtin_nontemporal_load((const f32x4*)(x + off)); yv[r][i] = __builtin_nontemporal_load((const u32x2*)(o2 + off)); }
;         }
.LBB0_601:
	s_or_b64 exec, exec, s[0:1]
	v_lshlrev_b64 v[32:33], 11, v[96:97]
	v_or_b32_e32 v32, v32, v100
	v_lshlrev_b64 v[36:37], 1, v[32:33]
	v_lshl_add_u64 v[34:35], v[32:33], 2, s[2:3]
	v_lshl_add_u64 v[38:39], s[4:5], 0, v[36:37]
	v_or_b32_e32 v40, 0x200, v36
	v_or_b32_e32 v42, 0x400, v36
	v_or_b32_e32 v36, 0x600, v36
	global_load_dwordx4 v[92:95], v[34:35], off nt
	global_load_dwordx4 v[80:83], v[34:35], off offset:1024 nt
	v_mov_b32_e32 v41, v37
	v_mov_b32_e32 v43, v37
	global_load_dwordx4 v[84:87], v[34:35], off offset:2048 nt
	global_load_dwordx4 v[64:67], v[34:35], off offset:3072 nt
	v_lshl_add_u64 v[34:35], s[4:5], 0, v[36:37]
	v_lshl_add_u64 v[40:41], s[4:5], 0, v[40:41]
	v_lshl_add_u64 v[42:43], s[4:5], 0, v[42:43]
	global_load_dwordx2 v[142:143], v[38:39], off
	global_load_dwordx2 v[140:141], v[40:41], off
	global_load_dwordx2 v[138:139], v[42:43], off
	global_load_dwordx2 v[132:133], v[34:35], off
	v_or_b32_e32 v34, 0x400, v32
	v_mov_b32_e32 v35, v33
	v_lshl_add_u64 v[36:37], v[34:35], 2, s[2:3]
	v_lshl_add_u64 v[34:35], v[34:35], 1, s[4:5]
	global_load_dwordx2 v[136:137], v[34:35], off
	v_or_b32_e32 v34, 0x500, v32
	v_mov_b32_e32 v35, v33
	global_load_dwordx4 v[88:91], v[36:37], off nt
	v_lshl_add_u64 v[36:37], v[34:35], 2, s[2:3]
	v_lshl_add_u64 v[34:35], v[34:35], 1, s[4:5]
	global_load_dwordx2 v[134:135], v[34:35], off
	v_or_b32_e32 v34, 0x600, v32
	v_mov_b32_e32 v35, v33
	global_load_dwordx4 v[76:79], v[36:37], off nt
	v_lshl_add_u64 v[36:37], v[34:35], 2, s[2:3]
	v_lshl_add_u64 v[34:35], v[34:35], 1, s[4:5]
	v_or_b32_e32 v32, 0x700, v32
	global_load_dwordx2 v[130:131], v[34:35], off
	v_lshl_add_u64 v[34:35], v[32:33], 2, s[2:3]
	v_lshl_add_u64 v[32:33], v[32:33], 1, s[4:5]
	global_load_dwordx4 v[72:75], v[36:37], off nt
	global_load_dwordx4 v[60:63], v[34:35], off nt
	global_load_dwordx2 v[128:129], v[32:33], off
	v_add_u32_e32 v118, 1, v96
	v_ashrrev_i32_e32 v119, 31, v118
	v_mov_b32_e32 v126, 0
	s_and_saveexec_b64 s[0:1], vcc
	s_cbranch_execz .LBB0_598
	v_lshlrev_b64 v[32:33], 7, v[118:119]
	v_lshl_add_u64 v[32:33], v[102:103], 0, v[32:33]
	global_load_dword v126, v[32:33], off
	s_branch .LBB0_598
